# attention C: 32 serialised relative-position-bias LDS reads per row issued in two batches of 16 (one wait per batch instead of one per read)
# speedup vs baseline: 1.0035x; 1.0035x over previous
.LBB0_518:
	v_cmp_ge_i32_e32 vcc, s86, v134
	v_cmp_lt_u32_e64 s[0:1], s86, v135
	s_add_i32 s72, s90, -1
	s_and_b64 s[0:1], vcc, s[0:1]
	s_andn2_b64 vcc, exec, s[0:1]
	s_and_b32 s89, s72, 1
	s_cbranch_vccnz .LBB0_524
	s_lshl_b32 s0, s89, 13
	v_add_u32_e32 v40, s0, v136
	v_add_u32_e32 v41, v40, v137
	ds_read_b128 v[32:35], v41 offset:0
	ds_read_b128 v[36:39], v41 offset:0x1000
	v_add_u32_e32 v41, v40, v138
	ds_read_b128 v[88:91], v41 offset:0
	ds_read_b128 v[92:95], v41 offset:0x1000
	v_add_u32_e32 v41, v40, v139
	ds_read_b128 v[96:99], v41 offset:0
	ds_read_b128 v[100:103], v41 offset:0x1000
	v_add_u32_e32 v40, v40, v140
	ds_read_b128 v[104:107], v40 offset:0
	ds_read_b128 v[108:111], v40 offset:0x1000
	s_waitcnt lgkmcnt(0)
	v_mfma_f32_32x32x16_bf16 v[48:63], v[32:35], v[64:67], 0
	v_mfma_f32_32x32x16_bf16 v[32:47], v[36:39], v[64:67], 0
	v_mfma_f32_32x32x16_bf16 v[48:63], v[88:91], v[68:71], v[48:63]
	v_mfma_f32_32x32x16_bf16 v[32:47], v[92:95], v[68:71], v[32:47]
	v_mfma_f32_32x32x16_bf16 v[48:63], v[96:99], v[72:75], v[48:63]
	v_mfma_f32_32x32x16_bf16 v[32:47], v[100:103], v[72:75], v[32:47]
	v_mfma_f32_32x32x16_bf16 v[48:63], v[104:107], v[80:83], v[48:63]
	v_mfma_f32_32x32x16_bf16 v[32:47], v[108:111], v[80:83], v[32:47]
	v_add_u32_e32 v177, s0, v141
	ds_read_b64_tr_b16 v[116:117], v177 offset:0
	ds_read_b64_tr_b16 v[118:119], v177 offset:0x400
	ds_read_b64_tr_b16 v[104:105], v177 offset:0x800
	ds_read_b64_tr_b16 v[106:107], v177 offset:0xc00
	ds_read_b64_tr_b16 v[96:97], v177 offset:0x1000
	ds_read_b64_tr_b16 v[98:99], v177 offset:0x1400
	ds_read_b64_tr_b16 v[92:93], v177 offset:0x1800
	ds_read_b64_tr_b16 v[94:95], v177 offset:0x1c00
	ds_read_b64_tr_b16 v[112:113], v177 offset:0x200
	ds_read_b64_tr_b16 v[114:115], v177 offset:0x600
	ds_read_b64_tr_b16 v[108:109], v177 offset:0xa00
	ds_read_b64_tr_b16 v[110:111], v177 offset:0xe00
	ds_read_b64_tr_b16 v[100:101], v177 offset:0x1200
	ds_read_b64_tr_b16 v[102:103], v177 offset:0x1600
	ds_read_b64_tr_b16 v[88:89], v177 offset:0x1a00
	ds_read_b64_tr_b16 v[90:91], v177 offset:0x1e00
	v_add_u32_e32 v192, s88, v173
	ds_read_b32 v192, v192
	v_add_u32_e32 v193, s88, v172
	ds_read_b32 v193, v193
	v_add_u32_e32 v204, s88, v171
	ds_read_b32 v204, v204
	v_add_u32_e32 v205, s88, v170
	ds_read_b32 v205, v205
	v_add_u32_e32 v206, s88, v169
	ds_read_b32 v206, v206
	v_add_u32_e32 v207, s88, v168
	ds_read_b32 v207, v207
	v_add_u32_e32 v208, s88, v167
	ds_read_b32 v208, v208
	v_add_u32_e32 v209, s88, v166
	ds_read_b32 v209, v209
	v_add_u32_e32 v210, s88, v165
	ds_read_b32 v210, v210
	v_add_u32_e32 v211, s88, v164
	ds_read_b32 v211, v211
	v_add_u32_e32 v212, s88, v163
	ds_read_b32 v212, v212
	v_add_u32_e32 v213, s88, v162
	ds_read_b32 v213, v213
	v_add_u32_e32 v214, s88, v161
	ds_read_b32 v214, v214
	v_add_u32_e32 v215, s88, v160
	ds_read_b32 v215, v215
	v_add_u32_e32 v216, s88, v159
	ds_read_b32 v216, v216
	v_add_u32_e32 v217, s88, v158
	ds_read_b32 v217, v217
	s_waitcnt lgkmcnt(0)
	v_add_f32_e32 v48, v48, v192
	v_add_u32_e32 v192, s88, v157
	ds_read_b32 v192, v192
	v_add_f32_e32 v32, v32, v193
	v_add_u32_e32 v193, s88, v156
	ds_read_b32 v193, v193
	v_cndmask_b32_e64 v48, v48, v232, s[6:7]
	v_add_f32_e32 v49, v49, v204
	v_add_u32_e32 v204, s88, v155
	ds_read_b32 v204, v204
	v_add_f32_e32 v33, v33, v205
	v_add_u32_e32 v205, s88, v154
	ds_read_b32 v205, v205
	v_cndmask_b32_e64 v49, v49, v232, s[10:11]
	v_add_f32_e32 v50, v50, v206
	v_add_u32_e32 v206, s88, v153
	ds_read_b32 v206, v206
	v_add_f32_e32 v34, v34, v207
	v_add_u32_e32 v207, s88, v152
	ds_read_b32 v207, v207
	v_cndmask_b32_e64 v50, v50, v232, s[14:15]
	v_add_f32_e32 v51, v51, v208
	v_add_u32_e32 v208, s88, v151
	ds_read_b32 v208, v208
	v_add_f32_e32 v35, v35, v209
	v_add_u32_e32 v209, s88, v150
	ds_read_b32 v209, v209
	v_cndmask_b32_e64 v51, v51, v232, s[18:19]
	v_add_f32_e32 v52, v52, v210
	v_add_u32_e32 v210, s88, v149
	ds_read_b32 v210, v210
	v_add_f32_e32 v36, v36, v211
	v_add_u32_e32 v211, s88, v148
	ds_read_b32 v211, v211
	v_cndmask_b32_e64 v52, v52, v232, s[22:23]
	v_add_f32_e32 v53, v53, v212
	v_add_u32_e32 v212, s88, v147
	ds_read_b32 v212, v212
	v_add_f32_e32 v37, v37, v213
	v_add_u32_e32 v213, s88, v146
	ds_read_b32 v213, v213
	v_cndmask_b32_e64 v53, v53, v232, s[26:27]
	v_add_f32_e32 v54, v54, v214
	v_add_u32_e32 v214, s88, v145
	ds_read_b32 v214, v214
	v_add_f32_e32 v38, v38, v215
	v_add_u32_e32 v215, s88, v144
	ds_read_b32 v215, v215
	v_cndmask_b32_e64 v54, v54, v232, s[30:31]
	v_add_f32_e32 v55, v55, v216
	v_add_u32_e32 v216, s88, v143
	ds_read_b32 v216, v216
	v_add_f32_e32 v39, v39, v217
	v_add_u32_e32 v217, s88, v142
	ds_read_b32 v217, v217
	v_cndmask_b32_e64 v55, v55, v232, s[36:37]
	s_waitcnt lgkmcnt(0)
	v_add_f32_e32 v56, v56, v192
	v_add_f32_e32 v40, v40, v193
	v_cndmask_b32_e64 v56, v232, v56, s[40:41]
	v_add_f32_e32 v57, v57, v204
	v_add_f32_e32 v41, v41, v205
	v_cndmask_b32_e64 v57, v232, v57, s[44:45]
	v_add_f32_e32 v58, v58, v206
	v_add_f32_e32 v42, v42, v207
	v_cndmask_b32_e64 v58, v232, v58, s[48:49]
	v_add_f32_e32 v59, v59, v208
	v_add_f32_e32 v43, v43, v209
	v_cndmask_b32_e64 v59, v232, v59, s[52:53]
	v_add_f32_e32 v60, v60, v210
	v_add_f32_e32 v44, v44, v211
	v_cndmask_b32_e64 v60, v232, v60, s[56:57]
	v_add_f32_e32 v61, v61, v212
	v_add_f32_e32 v45, v45, v213
	v_cndmask_b32_e64 v61, v232, v61, s[60:61]
	v_add_f32_e32 v62, v62, v214
	v_add_f32_e32 v46, v46, v215
	v_cndmask_b32_e64 v62, v232, v62, s[64:65]
	v_add_f32_e32 v63, v63, v216
	v_max_f32_e32 v177, v48, v49
	v_max3_f32 v177, v177, v50, v51
	v_max3_f32 v177, v177, v52, v53
	v_max3_f32 v177, v177, v54, v55
	v_max3_f32 v177, v177, v56, v57
	v_max3_f32 v177, v177, v58, v59
	v_cndmask_b32_e64 v63, v232, v63, s[68:69]
	v_max3_f32 v177, v177, v60, v61
	v_cndmask_b32_e64 v32, v232, v32, s[8:9]
	v_cndmask_b32_e64 v33, v232, v33, s[12:13]
	v_max3_f32 v177, v177, v62, v63
	v_cndmask_b32_e64 v34, v232, v34, s[16:17]
	v_cndmask_b32_e64 v35, v232, v35, s[20:21]
	v_max3_f32 v177, v177, v32, v33
	v_cndmask_b32_e64 v36, v232, v36, s[24:25]
	v_cndmask_b32_e64 v37, v232, v37, s[28:29]
	v_max3_f32 v177, v177, v34, v35
	v_cndmask_b32_e64 v38, v232, v38, s[34:35]
	v_cndmask_b32_e64 v39, v232, v39, s[38:39]
	v_max3_f32 v177, v177, v36, v37
	v_cndmask_b32_e64 v40, v232, v40, s[42:43]
	v_cndmask_b32_e64 v41, v232, v41, s[46:47]
	v_max3_f32 v177, v177, v38, v39
	v_cndmask_b32_e64 v42, v232, v42, s[50:51]
	v_cndmask_b32_e64 v43, v232, v43, s[54:55]
	v_max3_f32 v177, v177, v40, v41
	v_cndmask_b32_e64 v44, v232, v44, s[58:59]
	v_cndmask_b32_e64 v45, v232, v45, s[62:63]
	v_add_f32_e32 v47, v47, v217
	v_max3_f32 v177, v177, v42, v43
	v_cndmask_b32_e64 v46, v232, v46, s[66:67]
	v_cndmask_b32_e64 v47, v232, v47, s[70:71]
	v_max3_f32 v177, v177, v44, v45
	v_max3_f32 v177, v177, v46, v47
	v_mov_b32_e32 v178, v177
	s_nop 1
	v_permlane32_swap_b32_e32 v177, v178
	v_max_f32_e32 v178, v178, v178
	v_max_f32_e32 v177, v177, v177
	v_max_f32_e32 v177, v177, v178
	v_sub_f32_e32 v178, v177, v175
	v_cmp_ge_f32_e32 vcc, s85, v178
	s_cmp_eq_u64 vcc, exec
	v_max_f32_e32 v178, v175, v175
	s_cselect_b64 vcc, -1, 0
	v_max_f32_e32 v177, v178, v177
	v_sub_f32_e32 v178, v175, v177
	v_cndmask_b32_e32 v175, v177, v175, vcc
	v_mul_f32_e32 v177, 0xbe38aa3b, v175
	v_fmamk_f32 v48, v48, 0x3e38aa3b, v177
	v_exp_f32_e32 v179, v48
	v_fmamk_f32 v49, v49, 0x3e38aa3b, v177
	v_exp_f32_e32 v180, v49
	v_fmamk_f32 v49, v50, 0x3e38aa3b, v177
	v_exp_f32_e32 v181, v49
	v_fmamk_f32 v49, v51, 0x3e38aa3b, v177
	v_exp_f32_e32 v51, v49
	v_fmamk_f32 v49, v52, 0x3e38aa3b, v177
	v_add_f32_e32 v48, 0, v179
	v_exp_f32_e32 v52, v49
	v_fmamk_f32 v49, v53, 0x3e38aa3b, v177
	v_add_f32_e32 v48, v180, v48
	v_exp_f32_e32 v53, v49
	v_fmamk_f32 v49, v54, 0x3e38aa3b, v177
	v_add_f32_e32 v48, v181, v48
	v_exp_f32_e32 v54, v49
	v_fmamk_f32 v49, v55, 0x3e38aa3b, v177
	v_add_f32_e32 v48, v51, v48
	v_exp_f32_e32 v55, v49
	v_fmamk_f32 v49, v56, 0x3e38aa3b, v177
	v_add_f32_e32 v48, v52, v48
	v_exp_f32_e32 v56, v49
	v_fmamk_f32 v49, v57, 0x3e38aa3b, v177
	v_add_f32_e32 v48, v53, v48
	v_exp_f32_e32 v57, v49
	v_fmamk_f32 v49, v58, 0x3e38aa3b, v177
	v_add_f32_e32 v48, v54, v48
	v_exp_f32_e32 v58, v49
	v_fmamk_f32 v49, v59, 0x3e38aa3b, v177
	v_add_f32_e32 v48, v55, v48
	v_exp_f32_e32 v59, v49
	v_fmamk_f32 v49, v60, 0x3e38aa3b, v177
	v_add_f32_e32 v48, v56, v48
	v_exp_f32_e32 v60, v49
	v_fmamk_f32 v49, v61, 0x3e38aa3b, v177
	v_add_f32_e32 v48, v57, v48
	v_exp_f32_e32 v61, v49
	v_fmamk_f32 v49, v62, 0x3e38aa3b, v177
	v_add_f32_e32 v48, v58, v48
	v_exp_f32_e32 v62, v49
	v_fmamk_f32 v49, v63, 0x3e38aa3b, v177
	v_add_f32_e32 v48, v59, v48
	v_exp_f32_e32 v63, v49
	v_fmamk_f32 v32, v32, 0x3e38aa3b, v177
	v_add_f32_e32 v48, v60, v48
	v_exp_f32_e32 v32, v32
	v_fmamk_f32 v33, v33, 0x3e38aa3b, v177
	v_add_f32_e32 v48, v61, v48
	v_exp_f32_e32 v33, v33
	v_fmamk_f32 v34, v34, 0x3e38aa3b, v177
	v_add_f32_e32 v48, v62, v48
	v_exp_f32_e32 v34, v34
	v_fmamk_f32 v35, v35, 0x3e38aa3b, v177
	v_add_f32_e32 v48, v63, v48
	v_exp_f32_e32 v35, v35
	v_fmamk_f32 v36, v36, 0x3e38aa3b, v177
	v_add_f32_e32 v48, v32, v48
	v_exp_f32_e32 v182, v36
	v_fmamk_f32 v37, v37, 0x3e38aa3b, v177
	v_add_f32_e32 v48, v33, v48
	v_exp_f32_e32 v183, v37
	v_fmamk_f32 v37, v38, 0x3e38aa3b, v177
	v_add_f32_e32 v48, v34, v48
	v_exp_f32_e32 v184, v37
	v_fmamk_f32 v37, v39, 0x3e38aa3b, v177
	v_add_f32_e32 v48, v35, v48
	v_exp_f32_e32 v39, v37
	v_fmamk_f32 v37, v40, 0x3e38aa3b, v177
	v_add_f32_e32 v36, v182, v48
	v_exp_f32_e32 v185, v37
	v_fmamk_f32 v37, v41, 0x3e38aa3b, v177
	v_add_f32_e32 v36, v183, v36
	v_exp_f32_e32 v186, v37
	v_fmamk_f32 v37, v42, 0x3e38aa3b, v177
	v_add_f32_e32 v36, v184, v36
	v_exp_f32_e32 v187, v37
	v_fmamk_f32 v37, v43, 0x3e38aa3b, v177
	v_add_f32_e32 v36, v39, v36
	v_exp_f32_e32 v188, v37
	v_fmamk_f32 v37, v44, 0x3e38aa3b, v177
	v_add_f32_e32 v36, v185, v36
	v_exp_f32_e32 v189, v37
	v_fmamk_f32 v37, v45, 0x3e38aa3b, v177
	v_add_f32_e32 v36, v186, v36
	v_exp_f32_e32 v190, v37
	v_fmamk_f32 v37, v46, 0x3e38aa3b, v177
	v_add_f32_e32 v36, v187, v36
	v_exp_f32_e32 v191, v37
	v_fmac_f32_e32 v177, 0x3e38aa3b, v47
	v_mul_f32_e32 v178, 0x3e38aa3b, v178
	v_add_f32_e32 v36, v188, v36
	v_exp_f32_e32 v177, v177
	v_exp_f32_e32 v178, v178
	v_add_f32_e32 v36, v189, v36
	v_add_f32_e32 v36, v190, v36
	v_add_f32_e32 v36, v191, v36
	v_add_f32_e32 v49, v177, v36
	v_cndmask_b32_e64 v48, v178, 1.0, vcc
	v_mov_b32_e32 v50, v49
	v_cvt_pk_bf16_f32 v44, v179, v180
	v_cvt_pk_bf16_f32 v45, v181, v51
	v_cvt_pk_bf16_f32 v46, v52, v53
	v_cvt_pk_bf16_f32 v47, v54, v55
	v_cvt_pk_bf16_f32 v40, v56, v57
	v_cvt_pk_bf16_f32 v41, v58, v59
	v_cvt_pk_bf16_f32 v42, v60, v61
	v_cvt_pk_bf16_f32 v43, v62, v63
	v_cvt_pk_bf16_f32 v36, v32, v33
	v_cvt_pk_bf16_f32 v37, v34, v35
	v_cvt_pk_bf16_f32 v38, v182, v183
	v_cvt_pk_bf16_f32 v39, v184, v39
	v_cvt_pk_bf16_f32 v32, v185, v186
	v_cvt_pk_bf16_f32 v33, v187, v188
	v_cvt_pk_bf16_f32 v34, v189, v190
	v_cvt_pk_bf16_f32 v35, v191, v177
	s_nop 1
	v_permlane32_swap_b32_e32 v49, v50
	v_permlane32_swap_b32_e32 v44, v46
	v_permlane32_swap_b32_e32 v45, v47
	v_permlane32_swap_b32_e32 v40, v42
	v_permlane32_swap_b32_e32 v41, v43
	v_permlane32_swap_b32_e32 v36, v38
	v_permlane32_swap_b32_e32 v37, v39
	v_permlane32_swap_b32_e32 v32, v34
	v_permlane32_swap_b32_e32 v33, v35
	v_cmp_gt_f32_e32 vcc, 1.0, v48
	s_cbranch_vccz .LBB0_523
	s_and_saveexec_b64 s[0:1], s[4:5]
	ds_write_b32 v131, v48 offset:128
	s_or_b64 exec, exec, s[0:1]
	s_waitcnt lgkmcnt(0)
	v_add_u32_e32 v51, s79, v194
	ds_read_b128 v[52:55], v51 offset:224
	ds_read_b128 v[56:59], v51 offset:192
	ds_read_b128 v[60:63], v51 offset:160
	ds_read_b128 v[178:181], v51 offset:128
	s_waitcnt lgkmcnt(3)
	v_pk_mul_f32 v[12:13], v[12:13], v[52:53]
	s_waitcnt lgkmcnt(2)
	v_pk_mul_f32 v[8:9], v[8:9], v[56:57]
	s_waitcnt lgkmcnt(1)
	v_pk_mul_f32 v[4:5], v[4:5], v[60:61]
	s_waitcnt lgkmcnt(0)
	v_pk_mul_f32 v[0:1], v[0:1], v[178:179]
	v_pk_mul_f32 v[28:29], v[28:29], v[52:53]
	v_pk_mul_f32 v[24:25], v[24:25], v[56:57]
	v_pk_mul_f32 v[20:21], v[20:21], v[60:61]
	v_pk_mul_f32 v[14:15], v[14:15], v[54:55]
	v_pk_mul_f32 v[10:11], v[10:11], v[58:59]
	v_pk_mul_f32 v[6:7], v[6:7], v[62:63]
	v_pk_mul_f32 v[2:3], v[2:3], v[180:181]
	v_pk_mul_f32 v[30:31], v[30:31], v[54:55]
	v_pk_mul_f32 v[26:27], v[26:27], v[58:59]
	v_pk_mul_f32 v[22:23], v[22:23], v[62:63]
	v_pk_mul_f32 v[18:19], v[18:19], v[180:181]
	v_pk_mul_f32 v[16:17], v[16:17], v[178:179]
